# retention q/k GEMM epilogue: rotary table loads of the 4 fragments of a row issued together (8 waits per tile instead of 32)
# speedup vs baseline: 1.0063x; 1.0063x over previous
.LBB0_157:
	s_lshl_b32 s27, s6, 8
	v_add_u32_e32 v156, s27, v129
	v_mul_hi_i32 v136, v156, s87
	v_lshrrev_b32_e32 v152, 31, v136
	v_ashrrev_i32_e32 v136, 11, v136
	v_add_u32_e32 v136, v136, v152
	v_mul_i32_i24_e32 v136, 0x2100, v136
	v_sub_u32_e32 v180, v156, v136
	v_and_b32_e32 v136, 0xffffffc0, v180
	v_cmp_lt_i32_e64 s[10:11], s14, v180
	v_add_u32_e32 v181, 0xffffff00, v136
	s_and_saveexec_b64 s[6:7], s[10:11]
	s_cbranch_execz .LBB0_159
	v_or_b32_e32 v136, v181, v155
	v_lshl_add_u64 v[152:153], v[136:137], 3, s[16:17]
	global_load_dwordx4 v[182:185], v[152:153], off
	v_lshl_or_b32 v190, s4, 8, v149
	v_or_b32_e32 v208, 16, v190
	v_lshrrev_b32_e32 v210, 1, v208
	v_and_or_b32 v212, v210, 62, v181
	v_mov_b32_e32 v213, v137
	v_lshl_add_u64 v[214:215], v[212:213], 3, s[16:17]
	global_load_dwordx4 v[196:199], v[214:215], off
	v_and_b32_e32 v210, 15, v180
	v_lshlrev_b32_e32 v212, 3, v155
	v_lshl_or_b32 v214, v210, 9, v212
	global_load_dwordx4 v[200:203], v214, s[16:17]
	v_lshl_or_b32 v214, s4, 8, v149
	v_and_b32_e32 v216, 15, v180
	v_or_b32_e32 v218, 0x90, v214
	v_lshlrev_b32_e32 v222, 2, v218
	v_and_b32_e32 v222, 0x1f0, v222
	v_lshl_or_b32 v224, v216, 9, v222
	global_load_dwordx4 v[204:207], v224, s[16:17]
	s_waitcnt vmcnt(0)
	v_pk_mul_f32 v[152:153], v[124:125], v[182:183] op_sel:[1,1] op_sel_hi:[0,1]
	v_pk_mul_f32 v[186:187], v[124:125], v[182:183] op_sel_hi:[1,0]
	v_pk_fma_f32 v[124:125], v[124:125], v[182:183], v[152:153] op_sel_hi:[1,0,1]
	s_nop 0
	v_mul_f32_e32 v124, v127, v185
	v_pk_fma_f32 v[182:183], v[126:127], v[184:185], v[124:125] op_sel_hi:[1,1,0] neg_lo:[0,0,1] neg_hi:[0,0,1]
	v_mul_f32_e32 v124, v126, v185
	v_pk_fma_f32 v[184:185], v[126:127], v[184:185], v[124:125] op_sel:[1,0,0] op_sel_hi:[0,1,0]
	v_sub_f32_e32 v124, v186, v152
	v_mov_b32_e32 v126, v182
	v_mov_b32_e32 v127, v184
.LBB0_159:
	s_or_b64 exec, exec, s[6:7]
	v_ashrrev_i32_e32 v157, 31, v156
	v_lshl_or_b32 v152, s4, 8, v149
	v_lshlrev_b64 v[182:183], 12, v[156:157]
	v_pk_mul_f32 v[184:185], v[124:125], s[24:25] op_sel_hi:[1,0]
	v_pk_mul_f32 v[186:187], v[126:127], s[24:25] op_sel_hi:[1,0]
	v_cmp_lt_i32_e32 vcc, s15, v152
	v_ashrrev_i32_e32 v153, 31, v152
	s_nop 0
	v_cndmask_b32_e32 v127, v127, v187, vcc
	v_cndmask_b32_e32 v136, v126, v186, vcc
	v_cndmask_b32_e32 v126, v125, v185, vcc
	v_cndmask_b32_e32 v157, v124, v184, vcc
	v_lshl_add_u64 v[124:125], s[80:81], 0, v[182:183]
	v_lshl_add_u64 v[124:125], v[152:153], 1, v[124:125]
	v_cvt_pk_bf16_f32 v126, v157, v126
	v_cvt_pk_bf16_f32 v127, v136, v127
	v_or_b32_e32 v157, 16, v152
	global_store_dwordx2 v[124:125], v[126:127], off
	v_lshrrev_b32_e32 v126, 1, v157
	s_and_saveexec_b64 s[4:5], s[10:11]
	s_cbranch_execz .LBB0_161
	v_and_or_b32 v136, v126, 62, v181
	v_lshl_add_u64 v[182:183], v[136:137], 3, s[16:17]
	v_pk_mul_f32 v[186:187], v[120:121], v[196:197] op_sel:[1,1] op_sel_hi:[0,1]
	v_pk_mul_f32 v[188:189], v[120:121], v[196:197] op_sel_hi:[1,0]
	v_pk_fma_f32 v[120:121], v[120:121], v[196:197], v[186:187] op_sel_hi:[1,0,1]
	s_nop 0
	v_mul_f32_e32 v120, v123, v199
	v_pk_fma_f32 v[182:183], v[122:123], v[198:199], v[120:121] op_sel_hi:[1,1,0] neg_lo:[0,0,1] neg_hi:[0,0,1]
	v_mul_f32_e32 v120, v122, v199
	v_pk_fma_f32 v[184:185], v[122:123], v[198:199], v[120:121] op_sel:[1,0,0] op_sel_hi:[0,1,0]
	v_sub_f32_e32 v120, v188, v186
	v_mov_b32_e32 v122, v182
	v_mov_b32_e32 v123, v184
.LBB0_161:
	s_or_b64 exec, exec, s[4:5]
	v_and_b32_e32 v127, 15, v180
	v_pk_mul_f32 v[180:181], v[120:121], s[24:25] op_sel_hi:[1,0]
	v_pk_mul_f32 v[182:183], v[122:123], s[24:25] op_sel_hi:[1,0]
	v_cmp_lt_i32_e64 s[4:5], s15, v157
	s_nop 1
	v_cndmask_b32_e64 v123, v123, v183, s[4:5]
	v_cndmask_b32_e64 v122, v122, v182, s[4:5]
	v_cndmask_b32_e64 v121, v121, v181, s[4:5]
	v_cndmask_b32_e64 v120, v120, v180, s[4:5]
	v_cvt_pk_bf16_f32 v120, v120, v121
	v_cvt_pk_bf16_f32 v121, v122, v123
	global_store_dwordx2 v[124:125], v[120:121], off offset:32
	v_lshlrev_b32_e32 v120, 3, v155
	s_and_saveexec_b64 s[6:7], s[10:11]
	s_cbranch_execz .LBB0_163
	v_lshl_or_b32 v121, v127, 9, v120
	v_pk_mul_f32 v[122:123], v[116:117], v[200:201] op_sel:[1,1] op_sel_hi:[0,1]
	v_pk_mul_f32 v[184:185], v[116:117], v[200:201] op_sel_hi:[1,0]
	v_pk_fma_f32 v[116:117], v[116:117], v[200:201], v[122:123] op_sel_hi:[1,0,1]
	s_nop 0
	v_mul_f32_e32 v116, v119, v203
	v_pk_fma_f32 v[180:181], v[118:119], v[202:203], v[116:117] op_sel_hi:[1,1,0] neg_lo:[0,0,1] neg_hi:[0,0,1]
	v_mul_f32_e32 v116, v118, v203
	v_pk_fma_f32 v[182:183], v[118:119], v[202:203], v[116:117] op_sel:[1,0,0] op_sel_hi:[0,1,0]
	v_sub_f32_e32 v116, v184, v122
	v_mov_b32_e32 v118, v180
	v_mov_b32_e32 v119, v182
.LBB0_163:
	s_or_b64 exec, exec, s[6:7]
	v_or_b32_e32 v121, 0x80, v152
	v_pk_mul_f32 v[122:123], v[116:117], s[24:25] op_sel_hi:[1,0]
	v_pk_mul_f32 v[180:181], v[118:119], s[24:25] op_sel_hi:[1,0]
	v_cmp_lt_i32_e64 s[6:7], s15, v121
	s_nop 1
	v_cndmask_b32_e64 v119, v119, v181, s[6:7]
	v_cndmask_b32_e64 v118, v118, v180, s[6:7]
	v_cndmask_b32_e64 v117, v117, v123, s[6:7]
	v_cndmask_b32_e64 v116, v116, v122, s[6:7]
	v_cvt_pk_bf16_f32 v116, v116, v117
	v_cvt_pk_bf16_f32 v117, v118, v119
	global_store_dwordx2 v[124:125], v[116:117], off offset:256
	v_or_b32_e32 v117, 0x90, v152
	v_lshlrev_b32_e32 v116, 2, v117
	v_and_b32_e32 v116, 0x1f0, v116
	s_and_saveexec_b64 s[12:13], s[10:11]
	s_cbranch_execz .LBB0_165
	v_lshl_or_b32 v118, v127, 9, v116
	v_pk_mul_f32 v[118:119], v[112:113], v[204:205] op_sel:[1,1] op_sel_hi:[0,1]
	v_pk_mul_f32 v[122:123], v[112:113], v[204:205] op_sel_hi:[1,0]
	v_pk_fma_f32 v[112:113], v[112:113], v[204:205], v[118:119] op_sel_hi:[1,0,1]
	s_nop 0
	v_mul_f32_e32 v112, v115, v207
	v_pk_fma_f32 v[180:181], v[114:115], v[206:207], v[112:113] op_sel_hi:[1,1,0] neg_lo:[0,0,1] neg_hi:[0,0,1]
	v_mul_f32_e32 v112, v114, v207
	v_pk_fma_f32 v[182:183], v[114:115], v[206:207], v[112:113] op_sel:[1,0,0] op_sel_hi:[0,1,0]
	v_sub_f32_e32 v112, v122, v118
	v_mov_b32_e32 v114, v180
	v_mov_b32_e32 v115, v182
.LBB0_165:
	s_or_b64 exec, exec, s[12:13]
	v_pk_mul_f32 v[118:119], v[112:113], s[24:25] op_sel_hi:[1,0]
	v_pk_mul_f32 v[122:123], v[114:115], s[24:25] op_sel_hi:[1,0]
	v_cmp_lt_i32_e64 s[10:11], s15, v117
	s_nop 1
	v_cndmask_b32_e64 v115, v115, v123, s[10:11]
	v_cndmask_b32_e64 v114, v114, v122, s[10:11]
	v_cndmask_b32_e64 v113, v113, v119, s[10:11]
	v_cndmask_b32_e64 v112, v112, v118, s[10:11]
	v_cvt_pk_bf16_f32 v112, v112, v113
	v_cvt_pk_bf16_f32 v113, v114, v115
	global_store_dwordx2 v[124:125], v[112:113], off offset:288
	v_add_u32_e32 v112, s27, v160
	v_mul_hi_i32 v113, v112, s87
	v_lshrrev_b32_e32 v114, 31, v113
	v_ashrrev_i32_e32 v113, 11, v113
	v_add_u32_e32 v113, v113, v114
	v_mul_i32_i24_e32 v113, 0x2100, v113
	v_sub_u32_e32 v114, v112, v113
	v_and_b32_e32 v113, 0xffffffc0, v114
	v_cmp_lt_i32_e64 s[12:13], s14, v114
	v_add_u32_e32 v115, 0xffffff00, v113
	s_and_saveexec_b64 s[36:37], s[12:13]
	s_cbranch_execz .LBB0_167
	v_or_b32_e32 v136, v115, v155
	v_lshl_add_u64 v[118:119], v[136:137], 3, s[16:17]
	global_load_dwordx4 v[122:125], v[118:119], off
	v_and_or_b32 v190, v126, 62, v115
	v_mov_b32_e32 v191, v137
	v_lshl_add_u64 v[208:209], v[190:191], 3, s[16:17]
	global_load_dwordx4 v[196:199], v[208:209], off
	v_and_b32_e32 v210, 31, v114
	v_lshl_or_b32 v212, v210, 9, v120
	global_load_dwordx4 v[200:203], v212, s[16:17]
	v_and_b32_e32 v214, 31, v114
	v_lshl_or_b32 v216, v214, 9, v116
	global_load_dwordx4 v[204:207], v216, s[16:17]
	s_waitcnt vmcnt(0)
	v_pk_mul_f32 v[118:119], v[108:109], v[122:123] op_sel:[1,1] op_sel_hi:[0,1]
	v_pk_mul_f32 v[180:181], v[108:109], v[122:123] op_sel_hi:[1,0]
	v_pk_fma_f32 v[108:109], v[108:109], v[122:123], v[118:119] op_sel_hi:[1,0,1]
	s_nop 0
	v_mul_f32_e32 v108, v111, v125
	v_pk_fma_f32 v[122:123], v[110:111], v[124:125], v[108:109] op_sel_hi:[1,1,0] neg_lo:[0,0,1] neg_hi:[0,0,1]
	v_mul_f32_e32 v108, v110, v125
	v_pk_fma_f32 v[124:125], v[110:111], v[124:125], v[108:109] op_sel:[1,0,0] op_sel_hi:[0,1,0]
	v_sub_f32_e32 v108, v180, v118
	v_mov_b32_e32 v110, v122
	v_mov_b32_e32 v111, v124
.LBB0_167:
	s_or_b64 exec, exec, s[36:37]
	v_ashrrev_i32_e32 v113, 31, v112
	v_lshlrev_b64 v[112:113], 12, v[112:113]
	v_pk_mul_f32 v[118:119], v[108:109], s[24:25] op_sel_hi:[1,0]
	v_pk_mul_f32 v[122:123], v[110:111], s[24:25] op_sel_hi:[1,0]
	v_cndmask_b32_e32 v118, v108, v118, vcc
	v_cndmask_b32_e32 v111, v111, v123, vcc
	v_cndmask_b32_e32 v117, v110, v122, vcc
	v_cndmask_b32_e32 v110, v109, v119, vcc
	v_lshl_add_u64 v[108:109], s[80:81], 0, v[112:113]
	v_lshl_add_u64 v[108:109], v[152:153], 1, v[108:109]
	v_cvt_pk_bf16_f32 v110, v118, v110
	v_cvt_pk_bf16_f32 v111, v117, v111
	global_store_dwordx2 v[108:109], v[110:111], off
	s_and_saveexec_b64 s[36:37], s[12:13]
	s_cbranch_execz .LBB0_169
	v_and_or_b32 v136, v126, 62, v115
	v_lshl_add_u64 v[110:111], v[136:137], 3, s[16:17]
	v_pk_mul_f32 v[118:119], v[104:105], v[196:197] op_sel:[1,1] op_sel_hi:[0,1]
	v_pk_mul_f32 v[122:123], v[104:105], v[196:197] op_sel_hi:[1,0]
	v_pk_fma_f32 v[104:105], v[104:105], v[196:197], v[118:119] op_sel_hi:[1,0,1]
	s_nop 0
	v_mul_f32_e32 v104, v107, v199
	v_pk_fma_f32 v[110:111], v[106:107], v[198:199], v[104:105] op_sel_hi:[1,1,0] neg_lo:[0,0,1] neg_hi:[0,0,1]
	v_mul_f32_e32 v104, v106, v199
	v_pk_fma_f32 v[112:113], v[106:107], v[198:199], v[104:105] op_sel:[1,0,0] op_sel_hi:[0,1,0]
	v_sub_f32_e32 v104, v122, v118
	v_mov_b32_e32 v106, v110
	v_mov_b32_e32 v107, v112
.LBB0_169:
	s_or_b64 exec, exec, s[36:37]
	v_and_b32_e32 v110, 31, v114
	v_pk_mul_f32 v[112:113], v[104:105], s[24:25] op_sel_hi:[1,0]
	v_pk_mul_f32 v[114:115], v[106:107], s[24:25] op_sel_hi:[1,0]
	v_cndmask_b32_e64 v105, v105, v113, s[4:5]
	v_cndmask_b32_e64 v107, v107, v115, s[4:5]
	v_cndmask_b32_e64 v106, v106, v114, s[4:5]
	v_cndmask_b32_e64 v104, v104, v112, s[4:5]
	v_cvt_pk_bf16_f32 v104, v104, v105
	v_cvt_pk_bf16_f32 v105, v106, v107
	global_store_dwordx2 v[108:109], v[104:105], off offset:32
	s_and_saveexec_b64 s[36:37], s[12:13]
	s_cbranch_execz .LBB0_171
	v_lshl_or_b32 v104, v110, 9, v120
	v_pk_mul_f32 v[112:113], v[100:101], v[200:201] op_sel:[1,1] op_sel_hi:[0,1]
	v_pk_mul_f32 v[114:115], v[100:101], v[200:201] op_sel_hi:[1,0]
	v_pk_fma_f32 v[100:101], v[100:101], v[200:201], v[112:113] op_sel_hi:[1,0,1]
	s_nop 0
	v_mul_f32_e32 v100, v103, v203
	v_pk_fma_f32 v[104:105], v[102:103], v[202:203], v[100:101] op_sel_hi:[1,1,0] neg_lo:[0,0,1] neg_hi:[0,0,1]
	v_mul_f32_e32 v100, v102, v203
	v_pk_fma_f32 v[106:107], v[102:103], v[202:203], v[100:101] op_sel:[1,0,0] op_sel_hi:[0,1,0]
	v_sub_f32_e32 v100, v114, v112
	v_mov_b32_e32 v102, v104
	v_mov_b32_e32 v103, v106
.LBB0_171:
	s_or_b64 exec, exec, s[36:37]
	v_pk_mul_f32 v[104:105], v[100:101], s[24:25] op_sel_hi:[1,0]
	v_pk_mul_f32 v[106:107], v[102:103], s[24:25] op_sel_hi:[1,0]
	v_cndmask_b32_e64 v101, v101, v105, s[6:7]
	v_cndmask_b32_e64 v103, v103, v107, s[6:7]
	v_cndmask_b32_e64 v102, v102, v106, s[6:7]
	v_cndmask_b32_e64 v100, v100, v104, s[6:7]
	v_cvt_pk_bf16_f32 v100, v100, v101
	v_cvt_pk_bf16_f32 v101, v102, v103
	global_store_dwordx2 v[108:109], v[100:101], off offset:256
	s_and_saveexec_b64 s[36:37], s[12:13]
	s_cbranch_execz .LBB0_173
	v_lshl_or_b32 v100, v110, 9, v116
	v_pk_mul_f32 v[104:105], v[96:97], v[204:205] op_sel:[1,1] op_sel_hi:[0,1]
	v_pk_mul_f32 v[106:107], v[96:97], v[204:205] op_sel_hi:[1,0]
	v_pk_fma_f32 v[96:97], v[96:97], v[204:205], v[104:105] op_sel_hi:[1,0,1]
	s_nop 0
	v_mul_f32_e32 v96, v99, v207
	v_pk_fma_f32 v[100:101], v[98:99], v[206:207], v[96:97] op_sel_hi:[1,1,0] neg_lo:[0,0,1] neg_hi:[0,0,1]
	v_mul_f32_e32 v96, v98, v207
	v_pk_fma_f32 v[102:103], v[98:99], v[206:207], v[96:97] op_sel:[1,0,0] op_sel_hi:[0,1,0]
	v_sub_f32_e32 v96, v106, v104
	v_mov_b32_e32 v98, v100
	v_mov_b32_e32 v99, v102
.LBB0_173:
	s_or_b64 exec, exec, s[36:37]
	v_pk_mul_f32 v[100:101], v[96:97], s[24:25] op_sel_hi:[1,0]
	v_pk_mul_f32 v[102:103], v[98:99], s[24:25] op_sel_hi:[1,0]
	v_cndmask_b32_e64 v97, v97, v101, s[10:11]
	v_cndmask_b32_e64 v99, v99, v103, s[10:11]
	v_cndmask_b32_e64 v98, v98, v102, s[10:11]
	v_cndmask_b32_e64 v96, v96, v100, s[10:11]
	v_cvt_pk_bf16_f32 v96, v96, v97
	v_cvt_pk_bf16_f32 v97, v98, v99
	global_store_dwordx2 v[108:109], v[96:97], off offset:288
	v_add_u32_e32 v96, s27, v161
	v_mul_hi_i32 v97, v96, s87
	v_lshrrev_b32_e32 v98, 31, v97
	v_ashrrev_i32_e32 v97, 11, v97
	v_add_u32_e32 v97, v97, v98
	v_mul_i32_i24_e32 v97, 0x2100, v97
	v_sub_u32_e32 v98, v96, v97
	v_and_b32_e32 v97, 0xffffffc0, v98
	v_cmp_lt_i32_e64 s[12:13], s14, v98
	v_add_u32_e32 v99, 0xffffff00, v97
	s_and_saveexec_b64 s[36:37], s[12:13]
	s_cbranch_execz .LBB0_175
	v_or_b32_e32 v136, v99, v155
	v_lshl_add_u64 v[100:101], v[136:137], 3, s[16:17]
	global_load_dwordx4 v[100:103], v[100:101], off
	v_and_or_b32 v190, v126, 62, v99
	v_mov_b32_e32 v191, v137
	v_lshl_add_u64 v[208:209], v[190:191], 3, s[16:17]
	global_load_dwordx4 v[196:199], v[208:209], off
	v_and_b32_e32 v210, 47, v98
	v_lshl_or_b32 v212, v210, 9, v120
	global_load_dwordx4 v[200:203], v212, s[16:17]
	v_and_b32_e32 v214, 47, v98
	v_lshl_or_b32 v216, v214, 9, v116
	global_load_dwordx4 v[204:207], v216, s[16:17]
	s_waitcnt vmcnt(0)
	v_pk_mul_f32 v[104:105], v[92:93], v[100:101] op_sel:[1,1] op_sel_hi:[0,1]
	v_pk_mul_f32 v[106:107], v[92:93], v[100:101] op_sel_hi:[1,0]
	v_pk_fma_f32 v[92:93], v[92:93], v[100:101], v[104:105] op_sel_hi:[1,0,1]
	s_nop 0
	v_mul_f32_e32 v92, v95, v103
	v_pk_fma_f32 v[100:101], v[94:95], v[102:103], v[92:93] op_sel_hi:[1,1,0] neg_lo:[0,0,1] neg_hi:[0,0,1]
	v_mul_f32_e32 v92, v94, v103
	v_pk_fma_f32 v[102:103], v[94:95], v[102:103], v[92:93] op_sel:[1,0,0] op_sel_hi:[0,1,0]
	v_sub_f32_e32 v92, v106, v104
	v_mov_b32_e32 v94, v100
	v_mov_b32_e32 v95, v102
.LBB0_175:
	s_or_b64 exec, exec, s[36:37]
	v_ashrrev_i32_e32 v97, 31, v96
	v_lshlrev_b64 v[96:97], 12, v[96:97]
	v_pk_mul_f32 v[100:101], v[92:93], s[24:25] op_sel_hi:[1,0]
	v_pk_mul_f32 v[102:103], v[94:95], s[24:25] op_sel_hi:[1,0]
	v_cndmask_b32_e32 v100, v92, v100, vcc
	v_cndmask_b32_e32 v95, v95, v103, vcc
	v_cndmask_b32_e32 v102, v94, v102, vcc
	v_cndmask_b32_e32 v94, v93, v101, vcc
	v_lshl_add_u64 v[92:93], s[80:81], 0, v[96:97]
	v_lshl_add_u64 v[92:93], v[152:153], 1, v[92:93]
	v_cvt_pk_bf16_f32 v94, v100, v94
	v_cvt_pk_bf16_f32 v95, v102, v95
	global_store_dwordx2 v[92:93], v[94:95], off
	s_and_saveexec_b64 s[36:37], s[12:13]
	s_cbranch_execz .LBB0_177
	v_and_or_b32 v136, v126, 62, v99
	v_lshl_add_u64 v[94:95], v[136:137], 3, s[16:17]
	v_pk_mul_f32 v[100:101], v[88:89], v[196:197] op_sel:[1,1] op_sel_hi:[0,1]
	v_pk_mul_f32 v[102:103], v[88:89], v[196:197] op_sel_hi:[1,0]
	v_pk_fma_f32 v[88:89], v[88:89], v[196:197], v[100:101] op_sel_hi:[1,0,1]
	s_nop 0
	v_mul_f32_e32 v88, v91, v199
	v_pk_fma_f32 v[94:95], v[90:91], v[198:199], v[88:89] op_sel_hi:[1,1,0] neg_lo:[0,0,1] neg_hi:[0,0,1]
	v_mul_f32_e32 v88, v90, v199
	v_pk_fma_f32 v[96:97], v[90:91], v[198:199], v[88:89] op_sel:[1,0,0] op_sel_hi:[0,1,0]
	v_sub_f32_e32 v88, v102, v100
	v_mov_b32_e32 v90, v94
	v_mov_b32_e32 v91, v96
.LBB0_177:
	s_or_b64 exec, exec, s[36:37]
	v_and_b32_e32 v94, 47, v98
	v_pk_mul_f32 v[96:97], v[88:89], s[24:25] op_sel_hi:[1,0]
	v_pk_mul_f32 v[98:99], v[90:91], s[24:25] op_sel_hi:[1,0]
	v_cndmask_b32_e64 v89, v89, v97, s[4:5]
	v_cndmask_b32_e64 v91, v91, v99, s[4:5]
	v_cndmask_b32_e64 v90, v90, v98, s[4:5]
	v_cndmask_b32_e64 v88, v88, v96, s[4:5]
	v_cvt_pk_bf16_f32 v88, v88, v89
	v_cvt_pk_bf16_f32 v89, v90, v91
	global_store_dwordx2 v[92:93], v[88:89], off offset:32
	s_and_saveexec_b64 s[36:37], s[12:13]
	s_cbranch_execz .LBB0_179
	v_lshl_or_b32 v88, v94, 9, v120
	v_pk_mul_f32 v[96:97], v[84:85], v[200:201] op_sel:[1,1] op_sel_hi:[0,1]
	v_pk_mul_f32 v[98:99], v[84:85], v[200:201] op_sel_hi:[1,0]
	v_pk_fma_f32 v[84:85], v[84:85], v[200:201], v[96:97] op_sel_hi:[1,0,1]
	s_nop 0
	v_mul_f32_e32 v84, v87, v203
	v_pk_fma_f32 v[88:89], v[86:87], v[202:203], v[84:85] op_sel_hi:[1,1,0] neg_lo:[0,0,1] neg_hi:[0,0,1]
	v_mul_f32_e32 v84, v86, v203
	v_pk_fma_f32 v[90:91], v[86:87], v[202:203], v[84:85] op_sel:[1,0,0] op_sel_hi:[0,1,0]
	v_sub_f32_e32 v84, v98, v96
	v_mov_b32_e32 v86, v88
	v_mov_b32_e32 v87, v90
.LBB0_179:
	s_or_b64 exec, exec, s[36:37]
	v_pk_mul_f32 v[88:89], v[84:85], s[24:25] op_sel_hi:[1,0]
	v_pk_mul_f32 v[90:91], v[86:87], s[24:25] op_sel_hi:[1,0]
	v_cndmask_b32_e64 v85, v85, v89, s[6:7]
	v_cndmask_b32_e64 v87, v87, v91, s[6:7]
	v_cndmask_b32_e64 v86, v86, v90, s[6:7]
	v_cndmask_b32_e64 v84, v84, v88, s[6:7]
	v_cvt_pk_bf16_f32 v84, v84, v85
	v_cvt_pk_bf16_f32 v85, v86, v87
	global_store_dwordx2 v[92:93], v[84:85], off offset:256
	s_and_saveexec_b64 s[36:37], s[12:13]
	s_cbranch_execz .LBB0_181
	v_lshl_or_b32 v84, v94, 9, v116
	v_pk_mul_f32 v[88:89], v[80:81], v[204:205] op_sel:[1,1] op_sel_hi:[0,1]
	v_pk_mul_f32 v[90:91], v[80:81], v[204:205] op_sel_hi:[1,0]
	v_pk_fma_f32 v[80:81], v[80:81], v[204:205], v[88:89] op_sel_hi:[1,0,1]
	s_nop 0
	v_mul_f32_e32 v80, v83, v207
	v_pk_fma_f32 v[84:85], v[82:83], v[206:207], v[80:81] op_sel_hi:[1,1,0] neg_lo:[0,0,1] neg_hi:[0,0,1]
	v_mul_f32_e32 v80, v82, v207
	v_pk_fma_f32 v[86:87], v[82:83], v[206:207], v[80:81] op_sel:[1,0,0] op_sel_hi:[0,1,0]
	v_sub_f32_e32 v80, v90, v88
	v_mov_b32_e32 v82, v84
	v_mov_b32_e32 v83, v86
.LBB0_181:
	s_or_b64 exec, exec, s[36:37]
	v_pk_mul_f32 v[84:85], v[80:81], s[24:25] op_sel_hi:[1,0]
	v_pk_mul_f32 v[86:87], v[82:83], s[24:25] op_sel_hi:[1,0]
	v_cndmask_b32_e64 v81, v81, v85, s[10:11]
	v_cndmask_b32_e64 v83, v83, v87, s[10:11]
	v_cndmask_b32_e64 v82, v82, v86, s[10:11]
	v_cndmask_b32_e64 v80, v80, v84, s[10:11]
	v_cvt_pk_bf16_f32 v80, v80, v81
	v_cvt_pk_bf16_f32 v81, v82, v83
	global_store_dwordx2 v[92:93], v[80:81], off offset:288
	v_add_u32_e32 v80, s27, v162
	v_mul_hi_i32 v81, v80, s87
	v_lshrrev_b32_e32 v82, 31, v81
	v_ashrrev_i32_e32 v81, 11, v81
	v_add_u32_e32 v81, v81, v82
	v_mul_i32_i24_e32 v81, 0x2100, v81
	v_sub_u32_e32 v82, v80, v81
	v_and_b32_e32 v81, 0xffffffc0, v82
	v_cmp_lt_i32_e64 s[12:13], s14, v82
	v_add_u32_e32 v83, 0xffffff00, v81
	s_and_saveexec_b64 s[36:37], s[12:13]
	s_cbranch_execz .LBB0_183
	v_or_b32_e32 v136, v83, v155
	v_lshl_add_u64 v[84:85], v[136:137], 3, s[16:17]
	global_load_dwordx4 v[84:87], v[84:85], off
	v_and_or_b32 v190, v126, 62, v83
	v_mov_b32_e32 v191, v137
	v_lshl_add_u64 v[208:209], v[190:191], 3, s[16:17]
	global_load_dwordx4 v[196:199], v[208:209], off
	v_and_b32_e32 v210, 63, v82
	v_lshl_or_b32 v212, v210, 9, v120
	global_load_dwordx4 v[200:203], v212, s[16:17]
	v_and_b32_e32 v214, 63, v82
	v_lshl_or_b32 v216, v214, 9, v116
	global_load_dwordx4 v[204:207], v216, s[16:17]
	s_waitcnt vmcnt(0)
	v_pk_mul_f32 v[88:89], v[76:77], v[84:85] op_sel:[1,1] op_sel_hi:[0,1]
	v_pk_mul_f32 v[90:91], v[76:77], v[84:85] op_sel_hi:[1,0]
	v_pk_fma_f32 v[76:77], v[76:77], v[84:85], v[88:89] op_sel_hi:[1,0,1]
	s_nop 0
	v_mul_f32_e32 v76, v79, v87
	v_pk_fma_f32 v[84:85], v[78:79], v[86:87], v[76:77] op_sel_hi:[1,1,0] neg_lo:[0,0,1] neg_hi:[0,0,1]
	v_mul_f32_e32 v76, v78, v87
	v_pk_fma_f32 v[86:87], v[78:79], v[86:87], v[76:77] op_sel:[1,0,0] op_sel_hi:[0,1,0]
	v_sub_f32_e32 v76, v90, v88
	v_mov_b32_e32 v78, v84
	v_mov_b32_e32 v79, v86
.LBB0_183:
	s_or_b64 exec, exec, s[36:37]
	v_ashrrev_i32_e32 v81, 31, v80
	v_lshlrev_b64 v[80:81], 12, v[80:81]
	v_pk_mul_f32 v[84:85], v[76:77], s[24:25] op_sel_hi:[1,0]
	v_pk_mul_f32 v[86:87], v[78:79], s[24:25] op_sel_hi:[1,0]
	v_cndmask_b32_e32 v84, v76, v84, vcc
	v_cndmask_b32_e32 v79, v79, v87, vcc
	v_cndmask_b32_e32 v86, v78, v86, vcc
	v_cndmask_b32_e32 v78, v77, v85, vcc
	v_lshl_add_u64 v[76:77], s[80:81], 0, v[80:81]
	v_lshl_add_u64 v[76:77], v[152:153], 1, v[76:77]
	v_cvt_pk_bf16_f32 v78, v84, v78
	v_cvt_pk_bf16_f32 v79, v86, v79
	global_store_dwordx2 v[76:77], v[78:79], off
	s_and_saveexec_b64 s[36:37], s[12:13]
	s_cbranch_execz .LBB0_185
	v_and_or_b32 v136, v126, 62, v83
	v_lshl_add_u64 v[78:79], v[136:137], 3, s[16:17]
	v_pk_mul_f32 v[84:85], v[72:73], v[196:197] op_sel:[1,1] op_sel_hi:[0,1]
	v_pk_mul_f32 v[86:87], v[72:73], v[196:197] op_sel_hi:[1,0]
	v_pk_fma_f32 v[72:73], v[72:73], v[196:197], v[84:85] op_sel_hi:[1,0,1]
	s_nop 0
	v_mul_f32_e32 v72, v75, v199
	v_pk_fma_f32 v[78:79], v[74:75], v[198:199], v[72:73] op_sel_hi:[1,1,0] neg_lo:[0,0,1] neg_hi:[0,0,1]
	v_mul_f32_e32 v72, v74, v199
	v_pk_fma_f32 v[80:81], v[74:75], v[198:199], v[72:73] op_sel:[1,0,0] op_sel_hi:[0,1,0]
	v_sub_f32_e32 v72, v86, v84
	v_mov_b32_e32 v74, v78
	v_mov_b32_e32 v75, v80
.LBB0_185:
	s_or_b64 exec, exec, s[36:37]
	v_and_b32_e32 v78, 63, v82
	v_pk_mul_f32 v[80:81], v[72:73], s[24:25] op_sel_hi:[1,0]
	v_pk_mul_f32 v[82:83], v[74:75], s[24:25] op_sel_hi:[1,0]
	v_cndmask_b32_e64 v73, v73, v81, s[4:5]
	v_cndmask_b32_e64 v75, v75, v83, s[4:5]
	v_cndmask_b32_e64 v74, v74, v82, s[4:5]
	v_cndmask_b32_e64 v72, v72, v80, s[4:5]
	v_cvt_pk_bf16_f32 v72, v72, v73
	v_cvt_pk_bf16_f32 v73, v74, v75
	global_store_dwordx2 v[76:77], v[72:73], off offset:32
	s_and_saveexec_b64 s[36:37], s[12:13]
	s_cbranch_execz .LBB0_187
	v_lshl_or_b32 v72, v78, 9, v120
	v_pk_mul_f32 v[80:81], v[68:69], v[200:201] op_sel:[1,1] op_sel_hi:[0,1]
	v_pk_mul_f32 v[82:83], v[68:69], v[200:201] op_sel_hi:[1,0]
	v_pk_fma_f32 v[68:69], v[68:69], v[200:201], v[80:81] op_sel_hi:[1,0,1]
	s_nop 0
	v_mul_f32_e32 v68, v71, v203
	v_pk_fma_f32 v[72:73], v[70:71], v[202:203], v[68:69] op_sel_hi:[1,1,0] neg_lo:[0,0,1] neg_hi:[0,0,1]
	v_mul_f32_e32 v68, v70, v203
	v_pk_fma_f32 v[74:75], v[70:71], v[202:203], v[68:69] op_sel:[1,0,0] op_sel_hi:[0,1,0]
	v_sub_f32_e32 v68, v82, v80
	v_mov_b32_e32 v70, v72
	v_mov_b32_e32 v71, v74
.LBB0_187:
	s_or_b64 exec, exec, s[36:37]
	v_pk_mul_f32 v[72:73], v[68:69], s[24:25] op_sel_hi:[1,0]
	v_pk_mul_f32 v[74:75], v[70:71], s[24:25] op_sel_hi:[1,0]
	v_cndmask_b32_e64 v69, v69, v73, s[6:7]
	v_cndmask_b32_e64 v71, v71, v75, s[6:7]
	v_cndmask_b32_e64 v70, v70, v74, s[6:7]
	v_cndmask_b32_e64 v68, v68, v72, s[6:7]
	v_cvt_pk_bf16_f32 v68, v68, v69
	v_cvt_pk_bf16_f32 v69, v70, v71
	global_store_dwordx2 v[76:77], v[68:69], off offset:256
	s_and_saveexec_b64 s[36:37], s[12:13]
	s_cbranch_execz .LBB0_189
	v_lshl_or_b32 v68, v78, 9, v116
	v_pk_mul_f32 v[72:73], v[64:65], v[204:205] op_sel:[1,1] op_sel_hi:[0,1]
	v_pk_mul_f32 v[74:75], v[64:65], v[204:205] op_sel_hi:[1,0]
	v_pk_fma_f32 v[64:65], v[64:65], v[204:205], v[72:73] op_sel_hi:[1,0,1]
	s_nop 0
	v_mul_f32_e32 v64, v67, v207
	v_pk_fma_f32 v[68:69], v[66:67], v[206:207], v[64:65] op_sel_hi:[1,1,0] neg_lo:[0,0,1] neg_hi:[0,0,1]
	v_mul_f32_e32 v64, v66, v207
	v_pk_fma_f32 v[70:71], v[66:67], v[206:207], v[64:65] op_sel:[1,0,0] op_sel_hi:[0,1,0]
	v_sub_f32_e32 v64, v74, v72
	v_mov_b32_e32 v66, v68
	v_mov_b32_e32 v67, v70
.LBB0_189:
	s_or_b64 exec, exec, s[36:37]
	v_pk_mul_f32 v[68:69], v[64:65], s[24:25] op_sel_hi:[1,0]
	v_pk_mul_f32 v[70:71], v[66:67], s[24:25] op_sel_hi:[1,0]
	v_cndmask_b32_e64 v65, v65, v69, s[10:11]
	v_cndmask_b32_e64 v67, v67, v71, s[10:11]
	v_cndmask_b32_e64 v66, v66, v70, s[10:11]
	v_cndmask_b32_e64 v64, v64, v68, s[10:11]
	v_cvt_pk_bf16_f32 v64, v64, v65
	v_cvt_pk_bf16_f32 v65, v66, v67
	global_store_dwordx2 v[76:77], v[64:65], off offset:288
	v_add_u32_e32 v64, 0x80, v156
	v_mul_hi_i32 v65, v64, s87
	v_lshrrev_b32_e32 v66, 31, v65
	v_ashrrev_i32_e32 v65, 11, v65
	v_add_u32_e32 v65, v65, v66
	v_mul_i32_i24_e32 v65, 0x2100, v65
	v_sub_u32_e32 v66, v64, v65
	v_and_b32_e32 v65, 0xffffffc0, v66
	v_cmp_lt_i32_e64 s[12:13], s14, v66
	v_add_u32_e32 v67, 0xffffff00, v65
	s_and_saveexec_b64 s[36:37], s[12:13]
	s_cbranch_execz .LBB0_191
	v_or_b32_e32 v136, v67, v155
	v_lshl_add_u64 v[68:69], v[136:137], 3, s[16:17]
	global_load_dwordx4 v[68:71], v[68:69], off
	v_and_or_b32 v190, v126, 62, v67
	v_mov_b32_e32 v191, v137
	v_lshl_add_u64 v[208:209], v[190:191], 3, s[16:17]
	global_load_dwordx4 v[196:199], v[208:209], off
	v_and_b32_e32 v210, 15, v66
	v_lshl_or_b32 v212, v210, 9, v120
	global_load_dwordx4 v[200:203], v212, s[16:17]
	v_and_b32_e32 v214, 15, v66
	v_lshl_or_b32 v216, v214, 9, v116
	global_load_dwordx4 v[204:207], v216, s[16:17]
	s_waitcnt vmcnt(0)
	v_pk_mul_f32 v[72:73], v[60:61], v[68:69] op_sel:[1,1] op_sel_hi:[0,1]
	v_pk_mul_f32 v[74:75], v[60:61], v[68:69] op_sel_hi:[1,0]
	v_pk_fma_f32 v[60:61], v[60:61], v[68:69], v[72:73] op_sel_hi:[1,0,1]
	s_nop 0
	v_mul_f32_e32 v60, v63, v71
	v_pk_fma_f32 v[68:69], v[62:63], v[70:71], v[60:61] op_sel_hi:[1,1,0] neg_lo:[0,0,1] neg_hi:[0,0,1]
	v_mul_f32_e32 v60, v62, v71
	v_pk_fma_f32 v[70:71], v[62:63], v[70:71], v[60:61] op_sel:[1,0,0] op_sel_hi:[0,1,0]
	v_sub_f32_e32 v60, v74, v72
	v_mov_b32_e32 v62, v68
	v_mov_b32_e32 v63, v70
.LBB0_191:
	s_or_b64 exec, exec, s[36:37]
	v_ashrrev_i32_e32 v65, 31, v64
	v_lshlrev_b64 v[64:65], 12, v[64:65]
	v_pk_mul_f32 v[68:69], v[60:61], s[24:25] op_sel_hi:[1,0]
	v_pk_mul_f32 v[70:71], v[62:63], s[24:25] op_sel_hi:[1,0]
	v_cndmask_b32_e32 v68, v60, v68, vcc
	v_cndmask_b32_e32 v63, v63, v71, vcc
	v_cndmask_b32_e32 v70, v62, v70, vcc
	v_cndmask_b32_e32 v62, v61, v69, vcc
	v_lshl_add_u64 v[60:61], s[80:81], 0, v[64:65]
	v_lshl_add_u64 v[60:61], v[152:153], 1, v[60:61]
	v_cvt_pk_bf16_f32 v62, v68, v62
	v_cvt_pk_bf16_f32 v63, v70, v63
	global_store_dwordx2 v[60:61], v[62:63], off
	s_and_saveexec_b64 s[36:37], s[12:13]
	s_cbranch_execz .LBB0_193
	v_and_or_b32 v136, v126, 62, v67
	v_lshl_add_u64 v[62:63], v[136:137], 3, s[16:17]
	v_pk_mul_f32 v[68:69], v[56:57], v[196:197] op_sel:[1,1] op_sel_hi:[0,1]
	v_pk_mul_f32 v[70:71], v[56:57], v[196:197] op_sel_hi:[1,0]
	v_pk_fma_f32 v[56:57], v[56:57], v[196:197], v[68:69] op_sel_hi:[1,0,1]
	s_nop 0
	v_mul_f32_e32 v56, v59, v199
	v_pk_fma_f32 v[62:63], v[58:59], v[198:199], v[56:57] op_sel_hi:[1,1,0] neg_lo:[0,0,1] neg_hi:[0,0,1]
	v_mul_f32_e32 v56, v58, v199
	v_pk_fma_f32 v[64:65], v[58:59], v[198:199], v[56:57] op_sel:[1,0,0] op_sel_hi:[0,1,0]
	v_sub_f32_e32 v56, v70, v68
	v_mov_b32_e32 v58, v62
	v_mov_b32_e32 v59, v64
.LBB0_193:
	s_or_b64 exec, exec, s[36:37]
	v_and_b32_e32 v62, 15, v66
	v_pk_mul_f32 v[64:65], v[56:57], s[24:25] op_sel_hi:[1,0]
	v_pk_mul_f32 v[66:67], v[58:59], s[24:25] op_sel_hi:[1,0]
	v_cndmask_b32_e64 v57, v57, v65, s[4:5]
	v_cndmask_b32_e64 v59, v59, v67, s[4:5]
	v_cndmask_b32_e64 v58, v58, v66, s[4:5]
	v_cndmask_b32_e64 v56, v56, v64, s[4:5]
	v_cvt_pk_bf16_f32 v56, v56, v57
	v_cvt_pk_bf16_f32 v57, v58, v59
	global_store_dwordx2 v[60:61], v[56:57], off offset:32
	s_and_saveexec_b64 s[36:37], s[12:13]
	s_cbranch_execz .LBB0_195
	v_lshl_or_b32 v56, v62, 9, v120
	v_pk_mul_f32 v[64:65], v[52:53], v[200:201] op_sel:[1,1] op_sel_hi:[0,1]
	v_pk_mul_f32 v[66:67], v[52:53], v[200:201] op_sel_hi:[1,0]
	v_pk_fma_f32 v[52:53], v[52:53], v[200:201], v[64:65] op_sel_hi:[1,0,1]
	s_nop 0
	v_mul_f32_e32 v52, v55, v203
	v_pk_fma_f32 v[56:57], v[54:55], v[202:203], v[52:53] op_sel_hi:[1,1,0] neg_lo:[0,0,1] neg_hi:[0,0,1]
	v_mul_f32_e32 v52, v54, v203
	v_pk_fma_f32 v[58:59], v[54:55], v[202:203], v[52:53] op_sel:[1,0,0] op_sel_hi:[0,1,0]
	v_sub_f32_e32 v52, v66, v64
	v_mov_b32_e32 v54, v56
	v_mov_b32_e32 v55, v58
.LBB0_195:
	s_or_b64 exec, exec, s[36:37]
	v_pk_mul_f32 v[56:57], v[52:53], s[24:25] op_sel_hi:[1,0]
	v_pk_mul_f32 v[58:59], v[54:55], s[24:25] op_sel_hi:[1,0]
	v_cndmask_b32_e64 v53, v53, v57, s[6:7]
	v_cndmask_b32_e64 v55, v55, v59, s[6:7]
	v_cndmask_b32_e64 v54, v54, v58, s[6:7]
	v_cndmask_b32_e64 v52, v52, v56, s[6:7]
	v_cvt_pk_bf16_f32 v52, v52, v53
	v_cvt_pk_bf16_f32 v53, v54, v55
	global_store_dwordx2 v[60:61], v[52:53], off offset:256
	s_and_saveexec_b64 s[36:37], s[12:13]
	s_cbranch_execz .LBB0_197
	v_lshl_or_b32 v52, v62, 9, v116
	v_pk_mul_f32 v[56:57], v[48:49], v[204:205] op_sel:[1,1] op_sel_hi:[0,1]
	v_pk_mul_f32 v[58:59], v[48:49], v[204:205] op_sel_hi:[1,0]
	v_pk_fma_f32 v[48:49], v[48:49], v[204:205], v[56:57] op_sel_hi:[1,0,1]
	s_nop 0
	v_mul_f32_e32 v48, v51, v207
	v_pk_fma_f32 v[52:53], v[50:51], v[206:207], v[48:49] op_sel_hi:[1,1,0] neg_lo:[0,0,1] neg_hi:[0,0,1]
	v_mul_f32_e32 v48, v50, v207
	v_pk_fma_f32 v[54:55], v[50:51], v[206:207], v[48:49] op_sel:[1,0,0] op_sel_hi:[0,1,0]
	v_sub_f32_e32 v48, v58, v56
	v_mov_b32_e32 v50, v52
	v_mov_b32_e32 v51, v54
.LBB0_197:
	s_or_b64 exec, exec, s[36:37]
	v_pk_mul_f32 v[52:53], v[48:49], s[24:25] op_sel_hi:[1,0]
	v_pk_mul_f32 v[54:55], v[50:51], s[24:25] op_sel_hi:[1,0]
	v_cndmask_b32_e64 v49, v49, v53, s[10:11]
	v_cndmask_b32_e64 v51, v51, v55, s[10:11]
	v_cndmask_b32_e64 v50, v50, v54, s[10:11]
	v_cndmask_b32_e64 v48, v48, v52, s[10:11]
	v_cvt_pk_bf16_f32 v48, v48, v49
	v_cvt_pk_bf16_f32 v49, v50, v51
	global_store_dwordx2 v[60:61], v[48:49], off offset:288
	v_add_u32_e32 v48, 0x90, v156
	v_mul_hi_i32 v49, v48, s87
	v_lshrrev_b32_e32 v50, 31, v49
	v_ashrrev_i32_e32 v49, 11, v49
	v_add_u32_e32 v49, v49, v50
	v_mul_i32_i24_e32 v49, 0x2100, v49
	v_sub_u32_e32 v50, v48, v49
	v_and_b32_e32 v49, 0xffffffc0, v50
	v_cmp_lt_i32_e64 s[12:13], s14, v50
	v_add_u32_e32 v51, 0xffffff00, v49
	s_and_saveexec_b64 s[36:37], s[12:13]
	s_cbranch_execz .LBB0_199
	v_or_b32_e32 v136, v51, v155
	v_lshl_add_u64 v[52:53], v[136:137], 3, s[16:17]
	global_load_dwordx4 v[52:55], v[52:53], off
	v_and_or_b32 v190, v126, 62, v51
	v_mov_b32_e32 v191, v137
	v_lshl_add_u64 v[208:209], v[190:191], 3, s[16:17]
	global_load_dwordx4 v[196:199], v[208:209], off
	v_and_b32_e32 v210, 31, v50
	v_lshl_or_b32 v212, v210, 9, v120
	global_load_dwordx4 v[200:203], v212, s[16:17]
	v_and_b32_e32 v214, 31, v50
	v_lshl_or_b32 v216, v214, 9, v116
	global_load_dwordx4 v[204:207], v216, s[16:17]
	s_waitcnt vmcnt(0)
	v_pk_mul_f32 v[56:57], v[44:45], v[52:53] op_sel:[1,1] op_sel_hi:[0,1]
	v_pk_mul_f32 v[58:59], v[44:45], v[52:53] op_sel_hi:[1,0]
	v_pk_fma_f32 v[44:45], v[44:45], v[52:53], v[56:57] op_sel_hi:[1,0,1]
	s_nop 0
	v_mul_f32_e32 v44, v47, v55
	v_pk_fma_f32 v[52:53], v[46:47], v[54:55], v[44:45] op_sel_hi:[1,1,0] neg_lo:[0,0,1] neg_hi:[0,0,1]
	v_mul_f32_e32 v44, v46, v55
	v_pk_fma_f32 v[54:55], v[46:47], v[54:55], v[44:45] op_sel:[1,0,0] op_sel_hi:[0,1,0]
	v_sub_f32_e32 v44, v58, v56
	v_mov_b32_e32 v46, v52
	v_mov_b32_e32 v47, v54
.LBB0_199:
	s_or_b64 exec, exec, s[36:37]
	v_ashrrev_i32_e32 v49, 31, v48
	v_lshlrev_b64 v[48:49], 12, v[48:49]
	v_pk_mul_f32 v[52:53], v[44:45], s[24:25] op_sel_hi:[1,0]
	v_pk_mul_f32 v[54:55], v[46:47], s[24:25] op_sel_hi:[1,0]
	v_cndmask_b32_e32 v52, v44, v52, vcc
	v_cndmask_b32_e32 v47, v47, v55, vcc
	v_cndmask_b32_e32 v54, v46, v54, vcc
	v_cndmask_b32_e32 v46, v45, v53, vcc
	v_lshl_add_u64 v[44:45], s[80:81], 0, v[48:49]
	v_lshl_add_u64 v[44:45], v[152:153], 1, v[44:45]
	v_cvt_pk_bf16_f32 v46, v52, v46
	v_cvt_pk_bf16_f32 v47, v54, v47
	global_store_dwordx2 v[44:45], v[46:47], off
	s_and_saveexec_b64 s[36:37], s[12:13]
	s_cbranch_execz .LBB0_201
	v_and_or_b32 v136, v126, 62, v51
	v_lshl_add_u64 v[46:47], v[136:137], 3, s[16:17]
	v_pk_mul_f32 v[52:53], v[40:41], v[196:197] op_sel:[1,1] op_sel_hi:[0,1]
	v_pk_mul_f32 v[54:55], v[40:41], v[196:197] op_sel_hi:[1,0]
	v_pk_fma_f32 v[40:41], v[40:41], v[196:197], v[52:53] op_sel_hi:[1,0,1]
	s_nop 0
	v_mul_f32_e32 v40, v43, v199
	v_pk_fma_f32 v[46:47], v[42:43], v[198:199], v[40:41] op_sel_hi:[1,1,0] neg_lo:[0,0,1] neg_hi:[0,0,1]
	v_mul_f32_e32 v40, v42, v199
	v_pk_fma_f32 v[48:49], v[42:43], v[198:199], v[40:41] op_sel:[1,0,0] op_sel_hi:[0,1,0]
	v_sub_f32_e32 v40, v54, v52
	v_mov_b32_e32 v42, v46
	v_mov_b32_e32 v43, v48
.LBB0_201:
	s_or_b64 exec, exec, s[36:37]
	v_and_b32_e32 v46, 31, v50
	v_pk_mul_f32 v[48:49], v[40:41], s[24:25] op_sel_hi:[1,0]
	v_pk_mul_f32 v[50:51], v[42:43], s[24:25] op_sel_hi:[1,0]
	v_cndmask_b32_e64 v41, v41, v49, s[4:5]
	v_cndmask_b32_e64 v43, v43, v51, s[4:5]
	v_cndmask_b32_e64 v42, v42, v50, s[4:5]
	v_cndmask_b32_e64 v40, v40, v48, s[4:5]
	v_cvt_pk_bf16_f32 v40, v40, v41
	v_cvt_pk_bf16_f32 v41, v42, v43
	global_store_dwordx2 v[44:45], v[40:41], off offset:32
	s_and_saveexec_b64 s[36:37], s[12:13]
	s_cbranch_execz .LBB0_203
	v_lshl_or_b32 v40, v46, 9, v120
	v_pk_mul_f32 v[48:49], v[36:37], v[200:201] op_sel:[1,1] op_sel_hi:[0,1]
	v_pk_mul_f32 v[50:51], v[36:37], v[200:201] op_sel_hi:[1,0]
	v_pk_fma_f32 v[36:37], v[36:37], v[200:201], v[48:49] op_sel_hi:[1,0,1]
	s_nop 0
	v_mul_f32_e32 v36, v39, v203
	v_pk_fma_f32 v[40:41], v[38:39], v[202:203], v[36:37] op_sel_hi:[1,1,0] neg_lo:[0,0,1] neg_hi:[0,0,1]
	v_mul_f32_e32 v36, v38, v203
	v_pk_fma_f32 v[42:43], v[38:39], v[202:203], v[36:37] op_sel:[1,0,0] op_sel_hi:[0,1,0]
	v_sub_f32_e32 v36, v50, v48
	v_mov_b32_e32 v38, v40
	v_mov_b32_e32 v39, v42
.LBB0_203:
	s_or_b64 exec, exec, s[36:37]
	v_pk_mul_f32 v[40:41], v[36:37], s[24:25] op_sel_hi:[1,0]
	v_pk_mul_f32 v[42:43], v[38:39], s[24:25] op_sel_hi:[1,0]
	v_cndmask_b32_e64 v37, v37, v41, s[6:7]
	v_cndmask_b32_e64 v39, v39, v43, s[6:7]
	v_cndmask_b32_e64 v38, v38, v42, s[6:7]
	v_cndmask_b32_e64 v36, v36, v40, s[6:7]
	v_cvt_pk_bf16_f32 v36, v36, v37
	v_cvt_pk_bf16_f32 v37, v38, v39
	global_store_dwordx2 v[44:45], v[36:37], off offset:256
	s_and_saveexec_b64 s[36:37], s[12:13]
	s_cbranch_execz .LBB0_205
	v_lshl_or_b32 v36, v46, 9, v116
	v_pk_mul_f32 v[40:41], v[32:33], v[204:205] op_sel:[1,1] op_sel_hi:[0,1]
	v_pk_mul_f32 v[42:43], v[32:33], v[204:205] op_sel_hi:[1,0]
	v_pk_fma_f32 v[32:33], v[32:33], v[204:205], v[40:41] op_sel_hi:[1,0,1]
	s_nop 0
	v_mul_f32_e32 v32, v35, v207
	v_pk_fma_f32 v[36:37], v[34:35], v[206:207], v[32:33] op_sel_hi:[1,1,0] neg_lo:[0,0,1] neg_hi:[0,0,1]
	v_mul_f32_e32 v32, v34, v207
	v_pk_fma_f32 v[38:39], v[34:35], v[206:207], v[32:33] op_sel:[1,0,0] op_sel_hi:[0,1,0]
	v_sub_f32_e32 v32, v42, v40
	v_mov_b32_e32 v34, v36
	v_mov_b32_e32 v35, v38
.LBB0_205:
	s_or_b64 exec, exec, s[36:37]
	v_pk_mul_f32 v[36:37], v[32:33], s[24:25] op_sel_hi:[1,0]
	v_pk_mul_f32 v[38:39], v[34:35], s[24:25] op_sel_hi:[1,0]
	v_cndmask_b32_e64 v33, v33, v37, s[10:11]
	v_cndmask_b32_e64 v35, v35, v39, s[10:11]
	v_cndmask_b32_e64 v34, v34, v38, s[10:11]
	v_cndmask_b32_e64 v32, v32, v36, s[10:11]
	v_cvt_pk_bf16_f32 v32, v32, v33
	v_cvt_pk_bf16_f32 v33, v34, v35
	global_store_dwordx2 v[44:45], v[32:33], off offset:288
	v_add_u32_e32 v32, 0xa0, v156
	v_mul_hi_i32 v33, v32, s87
	v_lshrrev_b32_e32 v34, 31, v33
	v_ashrrev_i32_e32 v33, 11, v33
	v_add_u32_e32 v33, v33, v34
	v_mul_i32_i24_e32 v33, 0x2100, v33
	v_sub_u32_e32 v34, v32, v33
	v_and_b32_e32 v33, 0xffffffc0, v34
	v_cmp_lt_i32_e64 s[12:13], s14, v34
	v_add_u32_e32 v35, 0xffffff00, v33
	s_and_saveexec_b64 s[36:37], s[12:13]
	s_cbranch_execz .LBB0_207
	v_or_b32_e32 v136, v35, v155
	v_lshl_add_u64 v[36:37], v[136:137], 3, s[16:17]
	global_load_dwordx4 v[36:39], v[36:37], off
	v_and_or_b32 v190, v126, 62, v35
	v_mov_b32_e32 v191, v137
	v_lshl_add_u64 v[208:209], v[190:191], 3, s[16:17]
	global_load_dwordx4 v[196:199], v[208:209], off
	v_and_b32_e32 v210, 47, v34
	v_lshl_or_b32 v212, v210, 9, v120
	global_load_dwordx4 v[200:203], v212, s[16:17]
	v_and_b32_e32 v214, 47, v34
	v_lshl_or_b32 v216, v214, 9, v116
	global_load_dwordx4 v[204:207], v216, s[16:17]
	s_waitcnt vmcnt(0)
	v_pk_mul_f32 v[40:41], v[28:29], v[36:37] op_sel:[1,1] op_sel_hi:[0,1]
	v_pk_mul_f32 v[42:43], v[28:29], v[36:37] op_sel_hi:[1,0]
	v_pk_fma_f32 v[28:29], v[28:29], v[36:37], v[40:41] op_sel_hi:[1,0,1]
	s_nop 0
	v_mul_f32_e32 v28, v31, v39
	v_pk_fma_f32 v[36:37], v[30:31], v[38:39], v[28:29] op_sel_hi:[1,1,0] neg_lo:[0,0,1] neg_hi:[0,0,1]
	v_mul_f32_e32 v28, v30, v39
	v_pk_fma_f32 v[38:39], v[30:31], v[38:39], v[28:29] op_sel:[1,0,0] op_sel_hi:[0,1,0]
	v_sub_f32_e32 v28, v42, v40
	v_mov_b32_e32 v30, v36
	v_mov_b32_e32 v31, v38
.LBB0_207:
	s_or_b64 exec, exec, s[36:37]
	v_ashrrev_i32_e32 v33, 31, v32
	v_lshlrev_b64 v[32:33], 12, v[32:33]
	v_pk_mul_f32 v[36:37], v[28:29], s[24:25] op_sel_hi:[1,0]
	v_pk_mul_f32 v[38:39], v[30:31], s[24:25] op_sel_hi:[1,0]
	v_cndmask_b32_e32 v36, v28, v36, vcc
	v_cndmask_b32_e32 v31, v31, v39, vcc
	v_cndmask_b32_e32 v38, v30, v38, vcc
	v_cndmask_b32_e32 v30, v29, v37, vcc
	v_lshl_add_u64 v[28:29], s[80:81], 0, v[32:33]
	v_lshl_add_u64 v[28:29], v[152:153], 1, v[28:29]
	v_cvt_pk_bf16_f32 v30, v36, v30
	v_cvt_pk_bf16_f32 v31, v38, v31
	global_store_dwordx2 v[28:29], v[30:31], off
	s_and_saveexec_b64 s[36:37], s[12:13]
	s_cbranch_execz .LBB0_209
	v_and_or_b32 v136, v126, 62, v35
	v_lshl_add_u64 v[30:31], v[136:137], 3, s[16:17]
	v_pk_mul_f32 v[36:37], v[24:25], v[196:197] op_sel:[1,1] op_sel_hi:[0,1]
	v_pk_mul_f32 v[38:39], v[24:25], v[196:197] op_sel_hi:[1,0]
	v_pk_fma_f32 v[24:25], v[24:25], v[196:197], v[36:37] op_sel_hi:[1,0,1]
	s_nop 0
	v_mul_f32_e32 v24, v27, v199
	v_pk_fma_f32 v[30:31], v[26:27], v[198:199], v[24:25] op_sel_hi:[1,1,0] neg_lo:[0,0,1] neg_hi:[0,0,1]
	v_mul_f32_e32 v24, v26, v199
	v_pk_fma_f32 v[32:33], v[26:27], v[198:199], v[24:25] op_sel:[1,0,0] op_sel_hi:[0,1,0]
	v_sub_f32_e32 v24, v38, v36
	v_mov_b32_e32 v26, v30
	v_mov_b32_e32 v27, v32
.LBB0_209:
	s_or_b64 exec, exec, s[36:37]
	v_and_b32_e32 v30, 47, v34
	v_pk_mul_f32 v[32:33], v[24:25], s[24:25] op_sel_hi:[1,0]
	v_pk_mul_f32 v[34:35], v[26:27], s[24:25] op_sel_hi:[1,0]
	v_cndmask_b32_e64 v25, v25, v33, s[4:5]
	v_cndmask_b32_e64 v27, v27, v35, s[4:5]
	v_cndmask_b32_e64 v26, v26, v34, s[4:5]
	v_cndmask_b32_e64 v24, v24, v32, s[4:5]
	v_cvt_pk_bf16_f32 v24, v24, v25
	v_cvt_pk_bf16_f32 v25, v26, v27
	global_store_dwordx2 v[28:29], v[24:25], off offset:32
	s_and_saveexec_b64 s[36:37], s[12:13]
	s_cbranch_execz .LBB0_211
	v_lshl_or_b32 v24, v30, 9, v120
	v_pk_mul_f32 v[32:33], v[20:21], v[200:201] op_sel:[1,1] op_sel_hi:[0,1]
	v_pk_mul_f32 v[34:35], v[20:21], v[200:201] op_sel_hi:[1,0]
	v_pk_fma_f32 v[20:21], v[20:21], v[200:201], v[32:33] op_sel_hi:[1,0,1]
	s_nop 0
	v_mul_f32_e32 v20, v23, v203
	v_pk_fma_f32 v[24:25], v[22:23], v[202:203], v[20:21] op_sel_hi:[1,1,0] neg_lo:[0,0,1] neg_hi:[0,0,1]
	v_mul_f32_e32 v20, v22, v203
	v_pk_fma_f32 v[26:27], v[22:23], v[202:203], v[20:21] op_sel:[1,0,0] op_sel_hi:[0,1,0]
	v_sub_f32_e32 v20, v34, v32
	v_mov_b32_e32 v22, v24
	v_mov_b32_e32 v23, v26
.LBB0_211:
	s_or_b64 exec, exec, s[36:37]
	v_pk_mul_f32 v[24:25], v[20:21], s[24:25] op_sel_hi:[1,0]
	v_pk_mul_f32 v[26:27], v[22:23], s[24:25] op_sel_hi:[1,0]
	v_cndmask_b32_e64 v21, v21, v25, s[6:7]
	v_cndmask_b32_e64 v23, v23, v27, s[6:7]
	v_cndmask_b32_e64 v22, v22, v26, s[6:7]
	v_cndmask_b32_e64 v20, v20, v24, s[6:7]
	v_cvt_pk_bf16_f32 v20, v20, v21
	v_cvt_pk_bf16_f32 v21, v22, v23
	global_store_dwordx2 v[28:29], v[20:21], off offset:256
	s_and_saveexec_b64 s[36:37], s[12:13]
	s_cbranch_execz .LBB0_213
	v_lshl_or_b32 v20, v30, 9, v116
	v_pk_mul_f32 v[24:25], v[16:17], v[204:205] op_sel:[1,1] op_sel_hi:[0,1]
	v_pk_mul_f32 v[26:27], v[16:17], v[204:205] op_sel_hi:[1,0]
	v_pk_fma_f32 v[16:17], v[16:17], v[204:205], v[24:25] op_sel_hi:[1,0,1]
	s_nop 0
	v_mul_f32_e32 v16, v19, v207
	v_pk_fma_f32 v[20:21], v[18:19], v[206:207], v[16:17] op_sel_hi:[1,1,0] neg_lo:[0,0,1] neg_hi:[0,0,1]
	v_mul_f32_e32 v16, v18, v207
	v_pk_fma_f32 v[22:23], v[18:19], v[206:207], v[16:17] op_sel:[1,0,0] op_sel_hi:[0,1,0]
	v_sub_f32_e32 v16, v26, v24
	v_mov_b32_e32 v18, v20
	v_mov_b32_e32 v19, v22
.LBB0_213:
	s_or_b64 exec, exec, s[36:37]
	v_pk_mul_f32 v[20:21], v[16:17], s[24:25] op_sel_hi:[1,0]
	v_pk_mul_f32 v[22:23], v[18:19], s[24:25] op_sel_hi:[1,0]
	v_cndmask_b32_e64 v17, v17, v21, s[10:11]
	v_cndmask_b32_e64 v19, v19, v23, s[10:11]
	v_cndmask_b32_e64 v18, v18, v22, s[10:11]
	v_cndmask_b32_e64 v16, v16, v20, s[10:11]
	v_cvt_pk_bf16_f32 v16, v16, v17
	v_cvt_pk_bf16_f32 v17, v18, v19
	global_store_dwordx2 v[28:29], v[16:17], off offset:288
	v_add_u32_e32 v16, 0xb0, v156
	v_mul_hi_i32 v17, v16, s87
	v_lshrrev_b32_e32 v18, 31, v17
	v_ashrrev_i32_e32 v17, 11, v17
	v_add_u32_e32 v17, v17, v18
	v_mul_i32_i24_e32 v17, 0x2100, v17
	v_sub_u32_e32 v18, v16, v17
	v_and_b32_e32 v17, 0xffffffc0, v18
	v_cmp_lt_i32_e64 s[12:13], s14, v18
	v_add_u32_e32 v19, 0xffffff00, v17
	s_and_saveexec_b64 s[36:37], s[12:13]
	s_cbranch_execz .LBB0_215
	v_or_b32_e32 v136, v19, v155
	v_lshl_add_u64 v[20:21], v[136:137], 3, s[16:17]
	global_load_dwordx4 v[20:23], v[20:21], off
	v_and_or_b32 v190, v126, 62, v19
	v_mov_b32_e32 v191, v137
	v_lshl_add_u64 v[208:209], v[190:191], 3, s[16:17]
	global_load_dwordx4 v[196:199], v[208:209], off
	v_and_b32_e32 v210, 63, v18
	v_lshl_or_b32 v212, v210, 9, v120
	global_load_dwordx4 v[200:203], v212, s[16:17]
	v_and_b32_e32 v214, 63, v18
	v_lshl_or_b32 v216, v214, 9, v116
	global_load_dwordx4 v[204:207], v216, s[16:17]
	s_waitcnt vmcnt(0)
	v_pk_mul_f32 v[24:25], v[12:13], v[20:21] op_sel:[1,1] op_sel_hi:[0,1]
	v_pk_mul_f32 v[26:27], v[12:13], v[20:21] op_sel_hi:[1,0]
	v_pk_fma_f32 v[12:13], v[12:13], v[20:21], v[24:25] op_sel_hi:[1,0,1]
	s_nop 0
	v_mul_f32_e32 v12, v15, v23
	v_pk_fma_f32 v[20:21], v[14:15], v[22:23], v[12:13] op_sel_hi:[1,1,0] neg_lo:[0,0,1] neg_hi:[0,0,1]
	v_mul_f32_e32 v12, v14, v23
	v_pk_fma_f32 v[22:23], v[14:15], v[22:23], v[12:13] op_sel:[1,0,0] op_sel_hi:[0,1,0]
	v_sub_f32_e32 v12, v26, v24
	v_mov_b32_e32 v14, v20
	v_mov_b32_e32 v15, v22
.LBB0_215:
	s_or_b64 exec, exec, s[36:37]
	v_ashrrev_i32_e32 v17, 31, v16
	v_lshlrev_b64 v[16:17], 12, v[16:17]
	v_pk_mul_f32 v[20:21], v[12:13], s[24:25] op_sel_hi:[1,0]
	v_pk_mul_f32 v[22:23], v[14:15], s[24:25] op_sel_hi:[1,0]
	v_cndmask_b32_e32 v20, v12, v20, vcc
	v_cndmask_b32_e32 v15, v15, v23, vcc
	v_cndmask_b32_e32 v22, v14, v22, vcc
	v_cndmask_b32_e32 v14, v13, v21, vcc
	v_lshl_add_u64 v[12:13], s[80:81], 0, v[16:17]
	v_lshl_add_u64 v[12:13], v[152:153], 1, v[12:13]
	v_cvt_pk_bf16_f32 v14, v20, v14
	v_cvt_pk_bf16_f32 v15, v22, v15
	global_store_dwordx2 v[12:13], v[14:15], off
	s_and_saveexec_b64 s[36:37], s[12:13]
	s_cbranch_execz .LBB0_217
	v_and_or_b32 v136, v126, 62, v19
	v_lshl_add_u64 v[14:15], v[136:137], 3, s[16:17]
	v_pk_mul_f32 v[20:21], v[8:9], v[196:197] op_sel:[1,1] op_sel_hi:[0,1]
	v_pk_mul_f32 v[22:23], v[8:9], v[196:197] op_sel_hi:[1,0]
	v_pk_fma_f32 v[8:9], v[8:9], v[196:197], v[20:21] op_sel_hi:[1,0,1]
	s_nop 0
	v_mul_f32_e32 v8, v11, v199
	v_pk_fma_f32 v[14:15], v[10:11], v[198:199], v[8:9] op_sel_hi:[1,1,0] neg_lo:[0,0,1] neg_hi:[0,0,1]
	v_mul_f32_e32 v8, v10, v199
	v_pk_fma_f32 v[16:17], v[10:11], v[198:199], v[8:9] op_sel:[1,0,0] op_sel_hi:[0,1,0]
	v_sub_f32_e32 v8, v22, v20
	v_mov_b32_e32 v10, v14
	v_mov_b32_e32 v11, v16
.LBB0_217:
	s_or_b64 exec, exec, s[36:37]
	v_and_b32_e32 v14, 63, v18
	v_pk_mul_f32 v[16:17], v[8:9], s[24:25] op_sel_hi:[1,0]
	v_pk_mul_f32 v[18:19], v[10:11], s[24:25] op_sel_hi:[1,0]
	v_cndmask_b32_e64 v9, v9, v17, s[4:5]
	v_cndmask_b32_e64 v11, v11, v19, s[4:5]
	v_cndmask_b32_e64 v10, v10, v18, s[4:5]
	v_cndmask_b32_e64 v8, v8, v16, s[4:5]
	v_cvt_pk_bf16_f32 v8, v8, v9
	v_cvt_pk_bf16_f32 v9, v10, v11
	global_store_dwordx2 v[12:13], v[8:9], off offset:32
	s_and_saveexec_b64 s[4:5], s[12:13]
	s_cbranch_execz .LBB0_219
	v_lshl_or_b32 v8, v14, 9, v120
	v_pk_mul_f32 v[16:17], v[4:5], v[200:201] op_sel:[1,1] op_sel_hi:[0,1]
	v_pk_mul_f32 v[18:19], v[4:5], v[200:201] op_sel_hi:[1,0]
	v_pk_fma_f32 v[4:5], v[4:5], v[200:201], v[16:17] op_sel_hi:[1,0,1]
	s_nop 0
	v_mul_f32_e32 v4, v7, v203
	v_pk_fma_f32 v[8:9], v[6:7], v[202:203], v[4:5] op_sel_hi:[1,1,0] neg_lo:[0,0,1] neg_hi:[0,0,1]
	v_mul_f32_e32 v4, v6, v203
	v_pk_fma_f32 v[10:11], v[6:7], v[202:203], v[4:5] op_sel:[1,0,0] op_sel_hi:[0,1,0]
	v_sub_f32_e32 v4, v18, v16
	v_mov_b32_e32 v6, v8
	v_mov_b32_e32 v7, v10
.LBB0_219:
	s_or_b64 exec, exec, s[4:5]
	v_pk_mul_f32 v[8:9], v[4:5], s[24:25] op_sel_hi:[1,0]
	v_pk_mul_f32 v[10:11], v[6:7], s[24:25] op_sel_hi:[1,0]
	v_cndmask_b32_e64 v5, v5, v9, s[6:7]
	v_cndmask_b32_e64 v7, v7, v11, s[6:7]
	v_cndmask_b32_e64 v6, v6, v10, s[6:7]
	v_cndmask_b32_e64 v4, v4, v8, s[6:7]
	v_cvt_pk_bf16_f32 v4, v4, v5
	v_cvt_pk_bf16_f32 v5, v6, v7
	global_store_dwordx2 v[12:13], v[4:5], off offset:256
	s_and_saveexec_b64 s[4:5], s[12:13]
	s_cbranch_execz .LBB0_221
	v_lshl_or_b32 v4, v14, 9, v116
	v_pk_mul_f32 v[8:9], v[0:1], v[204:205] op_sel:[1,1] op_sel_hi:[0,1]
	v_pk_mul_f32 v[10:11], v[0:1], v[204:205] op_sel_hi:[1,0]
	v_pk_fma_f32 v[0:1], v[0:1], v[204:205], v[8:9] op_sel_hi:[1,0,1]
	s_nop 0
	v_mul_f32_e32 v0, v3, v207
	v_pk_fma_f32 v[4:5], v[2:3], v[206:207], v[0:1] op_sel_hi:[1,1,0] neg_lo:[0,0,1] neg_hi:[0,0,1]
	v_mul_f32_e32 v0, v2, v207
	v_pk_fma_f32 v[6:7], v[2:3], v[206:207], v[0:1] op_sel:[1,0,0] op_sel_hi:[0,1,0]
	v_sub_f32_e32 v0, v10, v8
	v_mov_b32_e32 v2, v4
	v_mov_b32_e32 v3, v6
